# phase 2a: skip the provably exhausted queue pull (barrier + atomic round trip + barrier) after a block's only item
# speedup vs baseline: 1.0153x; 1.0153x over previous
; __global__ void __launch_bounds__(256, 2) mega(Params p) {
;     ...
;     for (int rep = 0; rep < REP_2A; ++rep) {
;       bool first = true;
;       for (;;) {
;         int it;
;         if (first) { it = (int)blockIdx.x; first = false; }
;         else it = next_item(ctr + layer * 2 + 8 * rep, &slot) + (int)gridDim.x;
;         if (it >= 136 + 256) break;
;         it = (it < 256) ? (it + 136) : (it - 256);
;         if (it < 136) conv_unit(p, layer, it);
;         else if (it < 392) attn_prompt_item(p, layer, it - 136);
;         else attn_decode_item(p, layer, it - 392);
;       }
;       xcd_barrier(xb);
.LBB0_298:
	s_barrier
	s_mov_b64 s[0:1], exec
	v_readlane_b32 s6, v252, 1
	v_readlane_b32 s7, v252, 2
	v_readlane_b32 s64, v255, 38
	s_and_b64 s[6:7], s[0:1], s[6:7]
	v_readlane_b32 s65, v255, 39
	s_xor_b64 s[0:1], s[6:7], s[0:1]
	v_readlane_b32 s65, v255, 40
	s_mov_b32 s66, 0x20000
	s_mov_b32 s67, 0x40000
	s_mov_b32 s68, 0x60000
	v_readlane_b32 s69, v255, 50
	s_mov_b32 s70, 0x3fd744fd
	s_cmpk_gt_u32 s64, 0x187
	s_cbranch_scc0 .Lq2a_pull
	s_mov_b64 s[0:1], -1
	s_branch .LBB0_244
	s_nop 0
	s_nop 0
	s_nop 0
	s_nop 0
	s_nop 0
	s_nop 0
	s_nop 0
	s_nop 0
	s_nop 0
	s_nop 0
	s_nop 0
	s_nop 0
	s_nop 0
	s_nop 0
	s_nop 0
	s_nop 0
	s_nop 0
	s_nop 0
	s_nop 0
	s_nop 0
	s_nop 0
	s_nop 0
	s_nop 0
	s_nop 0
	s_nop 0
	s_nop 0
	s_nop 0
	s_nop 0
	s_nop 0
	s_nop 0
	s_nop 0
	s_nop 0
	s_nop 0
	s_nop 0
	s_nop 0
	s_nop 0
	s_nop 0
	s_nop 0
	s_nop 0
	s_nop 0
	s_nop 0
	s_nop 0
	s_nop 0
	s_nop 0
	s_nop 0
	s_nop 0
	s_nop 0
	s_nop 0
	s_nop 0
	s_nop 0
	s_nop 0
	s_nop 0
	s_nop 0
	s_nop 0
	s_nop 0
	s_nop 0
	s_nop 0
	s_nop 0
	s_nop 0
	s_nop 0
.Lq2a_pull:
	s_mov_b64 exec, s[6:7]
	s_cbranch_execz .LBB0_243
	s_mov_b64 s[8:9], exec
	s_waitcnt vmcnt(6)
	v_mbcnt_lo_u32_b32 v0, s8, 0
	v_mbcnt_hi_u32_b32 v0, s9, v0
	v_cmp_eq_u32_e32 vcc, 0, v0
	s_and_saveexec_b64 s[6:7], vcc
	s_cbranch_execz .LBB0_242
	s_bcnt1_i32_b64 s2, s[8:9]
	v_readlane_b32 s8, v255, 43
	v_mov_b32_e32 v1, s2
	v_readlane_b32 s9, v255, 44
	s_nop 4
	global_atomic_add v1, v161, v1, s[8:9] sc0
	s_branch .LBB0_242
